# grid barrier: all workgroups wait on the cross-XCC arrival counter reaching its target (no separate release generation hop)
# baseline (speedup 1.0000x reference)
; __device__ __forceinline__ unsigned xb_ld(unsigned* p)              { return __hip_atomic_load(p, __ATOMIC_RELAXED, __HIP_MEMORY_SCOPE_AGENT); }
; __device__ __forceinline__ unsigned xb_add(unsigned* p, unsigned v) { return __hip_atomic_fetch_add(p, v, __ATOMIC_RELAXED, __HIP_MEMORY_SCOPE_AGENT); }
; #define XB_SPIN(cond, bar) do { unsigned _sp = 0; while (cond) { __builtin_amdgcn_s_sleep(1); \
;     if ((++_sp & 255u) == 0u) { if (xb_ld(&(bar)[XB_TMO])) break; if (_sp > XB_SPIN_CAP) { atomicAdd(&(bar)[XB_TMO], 1u); break; } } } } while (0)
; __device__ __forceinline__ void xcd_barrier(const XcdBarrier& b, const bool leader  ) {
;     ...
;         const unsigned old = xb_add(&bar[XB_XSUB(b.x)], 1u);
;         const unsigned gen = old / nloc;
;         if (old + 1u == (gen + 1u) * nloc) {
;             __builtin_amdgcn_fence(__ATOMIC_RELEASE, "agent");
;             asm volatile("s_waitcnt vmcnt(0)" ::: "memory");
;             const unsigned og = xb_add(&bar[XB_TOP], 1u);
;             const unsigned tg = og / nx;
;             if (og + 1u == (tg + 1u) * nx) xb_add(&bar[XB_TOPGEN], 1u);
;             else XB_SPIN(xb_ld(&bar[XB_TOPGEN]) == tg, bar);
;             __builtin_amdgcn_fence(__ATOMIC_ACQUIRE, "agent");
;             xb_add(&bar[XB_XGEN(b.x)], 1u);
;             asm volatile("s_waitcnt vmcnt(0)" ::: "memory");
;         } else {
;             XB_SPIN(xb_ld(&bar[XB_XGEN(b.x)]) == gen, bar);
;             __builtin_amdgcn_fence(__ATOMIC_ACQUIRE, "agent");
;             asm volatile("s_waitcnt vmcnt(0)" ::: "memory");
;         }
.LBB0_86:
	s_or_b64 exec, exec, s[12:13]
	v_cvt_f32_u32_e32 v4, v2
	s_waitcnt vmcnt(0)
	v_readfirstlane_b32 s10, v3
	s_add_u32 s2, s2, 0x2400
	s_addc_u32 s3, s3, 0
	v_rcp_iflag_f32_e32 v4, v4
	v_add_u32_e32 v5, s10, v1
	v_mul_f32_e32 v3, 0x4f7ffffe, v4
	v_cvt_u32_f32_e32 v3, v3
	v_sub_u32_e32 v4, 0, v2
	v_mul_lo_u32 v1, v4, v3
	v_mul_hi_u32 v1, v3, v1
	v_add_u32_e32 v1, v3, v1
	v_mul_hi_u32 v1, v5, v1
	v_mul_lo_u32 v3, v1, v2
	v_sub_u32_e32 v3, v5, v3
	v_add_u32_e32 v4, 1, v1
	v_cmp_ge_u32_e32 vcc, v3, v2
	s_nop 1
	v_cndmask_b32_e32 v1, v1, v4, vcc
	v_sub_u32_e32 v4, v3, v2
	v_cndmask_b32_e32 v3, v3, v4, vcc
	v_add_u32_e32 v4, 1, v1
	v_cmp_ge_u32_e32 vcc, v3, v2
	v_add_u32_e32 v3, 1, v5
	s_nop 0
	v_cndmask_b32_e32 v1, v1, v4, vcc
	v_mul_lo_u32 v4, v2, v1
	v_add_u32_e32 v2, v4, v2
	v_cmp_ne_u32_e32 vcc, v3, v2
	s_and_saveexec_b64 s[10:11], vcc
	s_xor_b64 s[10:11], exec, s[10:11]
	s_cbranch_execz .LBB0_100
	s_waitcnt lgkmcnt(0)
	v_add_u32_e32 v1, 1, v1
	v_mul_lo_u32 v1, v1, v0
	s_add_u32 s2, s8, 0x7400
	s_addc_u32 s3, s9, 0
	v_mov_b32_e32 v0, 0
	global_load_dword v2, v0, s[2:3] sc1
	s_waitcnt vmcnt(0)
	v_cmp_lt_u32_e32 vcc, v2, v1
	s_and_saveexec_b64 s[12:13], vcc
	s_cbranch_execz .LBB0_99
	s_mov_b32 s20, 1
	s_mov_b64 s[14:15], 0
	s_branch .LBB0_90

; __device__ __forceinline__ unsigned xb_ld(unsigned* p)              { return __hip_atomic_load(p, __ATOMIC_RELAXED, __HIP_MEMORY_SCOPE_AGENT); }
; #define XB_SPIN(cond, bar) do { unsigned _sp = 0; while (cond) { __builtin_amdgcn_s_sleep(1); \
;     if ((++_sp & 255u) == 0u) { if (xb_ld(&(bar)[XB_TMO])) break; if (_sp > XB_SPIN_CAP) { atomicAdd(&(bar)[XB_TMO], 1u); break; } } } } while (0)
; __device__ __forceinline__ void xcd_barrier(const XcdBarrier& b, const bool leader  ) {
;     ...
;             XB_SPIN(xb_ld(&bar[XB_XGEN(b.x)]) == gen, bar);
.LBB0_92:
	global_load_dword v2, v0, s[2:3] sc1
	s_add_i32 s20, s20, 1
	s_mov_b64 s[24:25], -1
	s_waitcnt vmcnt(0)
	v_cmp_ge_u32_e32 vcc, v2, v1
	s_orn2_b64 s[18:19], vcc, exec
	s_branch .LBB0_89

; __device__ __forceinline__ unsigned xb_ld(unsigned* p)              { return __hip_atomic_load(p, __ATOMIC_RELAXED, __HIP_MEMORY_SCOPE_AGENT); }
; __device__ __forceinline__ unsigned xb_add(unsigned* p, unsigned v) { return __hip_atomic_fetch_add(p, v, __ATOMIC_RELAXED, __HIP_MEMORY_SCOPE_AGENT); }
; #define XB_SPIN(cond, bar) do { unsigned _sp = 0; while (cond) { __builtin_amdgcn_s_sleep(1); \
;     if ((++_sp & 255u) == 0u) { if (xb_ld(&(bar)[XB_TMO])) break; if (_sp > XB_SPIN_CAP) { atomicAdd(&(bar)[XB_TMO], 1u); break; } } } } while (0)
; __device__ __forceinline__ void xcd_barrier(const XcdBarrier& b, const bool leader  ) {
;     ...
;             const unsigned og = xb_add(&bar[XB_TOP], 1u);
;             const unsigned tg = og / nx;
;             if (og + 1u == (tg + 1u) * nx) xb_add(&bar[XB_TOPGEN], 1u);
;             else XB_SPIN(xb_ld(&bar[XB_TOPGEN]) == tg, bar);
.LBB0_103:
	s_or_b64 exec, exec, s[12:13]
	v_cvt_f32_u32_e32 v3, v0
	s_waitcnt vmcnt(0)
	v_readfirstlane_b32 s10, v2
	s_add_u32 s8, s8, 0x7500
	s_addc_u32 s9, s9, 0
	v_rcp_iflag_f32_e32 v3, v3
	v_add_u32_e32 v1, s10, v1
	s_mov_b64 s[12:13], 0
	v_mul_f32_e32 v2, 0x4f7ffffe, v3
	v_cvt_u32_f32_e32 v2, v2
	v_sub_u32_e32 v3, 0, v0
	v_mul_lo_u32 v3, v3, v2
	v_mul_hi_u32 v3, v2, v3
	v_add_u32_e32 v2, v2, v3
	v_mul_hi_u32 v2, v1, v2
	v_mul_lo_u32 v3, v2, v0
	v_sub_u32_e32 v3, v1, v3
	v_add_u32_e32 v4, 1, v2
	v_cmp_ge_u32_e32 vcc, v3, v0
	v_add_u32_e32 v1, 1, v1
	s_nop 0
	v_cndmask_b32_e32 v2, v2, v4, vcc
	v_sub_u32_e32 v4, v3, v0
	v_cndmask_b32_e32 v3, v3, v4, vcc
	v_add_u32_e32 v4, 1, v2
	v_cmp_ge_u32_e32 vcc, v3, v0
	s_nop 1
	v_cndmask_b32_e32 v2, v2, v4, vcc
	v_mul_lo_u32 v3, v0, v2
	v_add_u32_e32 v0, v3, v0
	v_cmp_ne_u32_e32 vcc, v1, v0
	v_mov_b32_e32 v2, v0
	v_mov_b64_e32 v[0:1], s[8:9]
	s_and_saveexec_b64 s[10:11], vcc
	s_cbranch_execz .LBB0_115
	v_mov_b32_e32 v0, 0
	global_load_dword v1, v0, s[8:9] offset:-256 sc1
	s_mov_b64 s[14:15], 0
	s_waitcnt vmcnt(0)
	v_cmp_lt_u32_e32 vcc, v1, v2
	s_and_saveexec_b64 s[12:13], vcc
	s_cbranch_execz .LBB0_114
	s_mov_b32 s20, 1
	s_branch .LBB0_107

; __device__ __forceinline__ unsigned xb_ld(unsigned* p)              { return __hip_atomic_load(p, __ATOMIC_RELAXED, __HIP_MEMORY_SCOPE_AGENT); }
; #define XB_SPIN(cond, bar) do { unsigned _sp = 0; while (cond) { __builtin_amdgcn_s_sleep(1); \
;     if ((++_sp & 255u) == 0u) { if (xb_ld(&(bar)[XB_TMO])) break; if (_sp > XB_SPIN_CAP) { atomicAdd(&(bar)[XB_TMO], 1u); break; } } } } while (0)
; __device__ __forceinline__ void xcd_barrier(const XcdBarrier& b, const bool leader  ) {
;     ...
;             else XB_SPIN(xb_ld(&bar[XB_TOPGEN]) == tg, bar);
.LBB0_109:
	global_load_dword v1, v0, s[8:9] offset:-256 sc1
	s_add_i32 s20, s20, 1
	s_mov_b64 s[18:19], -1
	s_waitcnt vmcnt(0)
	v_cmp_ge_u32_e32 vcc, v1, v2
	s_orn2_b64 s[26:27], vcc, exec
	s_branch .LBB0_106

; __device__ __forceinline__ unsigned xb_ld(unsigned* p)              { return __hip_atomic_load(p, __ATOMIC_RELAXED, __HIP_MEMORY_SCOPE_AGENT); }
; __device__ __forceinline__ unsigned xb_add(unsigned* p, unsigned v) { return __hip_atomic_fetch_add(p, v, __ATOMIC_RELAXED, __HIP_MEMORY_SCOPE_AGENT); }
; #define XB_SPIN(cond, bar) do { unsigned _sp = 0; while (cond) { __builtin_amdgcn_s_sleep(1); \
;     if ((++_sp & 255u) == 0u) { if (xb_ld(&(bar)[XB_TMO])) break; if (_sp > XB_SPIN_CAP) { atomicAdd(&(bar)[XB_TMO], 1u); break; } } } } while (0)
; __device__ __forceinline__ void xcd_barrier(const XcdBarrier& b, const bool leader  ) {
;     ...
;         const unsigned old = xb_add(&bar[XB_XSUB(b.x)], 1u);
;         const unsigned gen = old / nloc;
;         if (old + 1u == (gen + 1u) * nloc) {
;             __builtin_amdgcn_fence(__ATOMIC_RELEASE, "agent");
;             asm volatile("s_waitcnt vmcnt(0)" ::: "memory");
;             const unsigned og = xb_add(&bar[XB_TOP], 1u);
;             const unsigned tg = og / nx;
;             if (og + 1u == (tg + 1u) * nx) xb_add(&bar[XB_TOPGEN], 1u);
;             else XB_SPIN(xb_ld(&bar[XB_TOPGEN]) == tg, bar);
;             __builtin_amdgcn_fence(__ATOMIC_ACQUIRE, "agent");
;             xb_add(&bar[XB_XGEN(b.x)], 1u);
;             asm volatile("s_waitcnt vmcnt(0)" ::: "memory");
;         } else {
;             XB_SPIN(xb_ld(&bar[XB_XGEN(b.x)]) == gen, bar);
;             __builtin_amdgcn_fence(__ATOMIC_ACQUIRE, "agent");
;             asm volatile("s_waitcnt vmcnt(0)" ::: "memory");
;         }
.LBB0_153:
	s_or_b64 exec, exec, s[12:13]
	v_cvt_f32_u32_e32 v4, v2
	s_waitcnt vmcnt(0)
	v_readfirstlane_b32 s10, v3
	s_add_u32 s8, s8, 0x2400
	s_addc_u32 s9, s9, 0
	v_rcp_iflag_f32_e32 v4, v4
	v_add_u32_e32 v5, s10, v1
	v_mul_f32_e32 v3, 0x4f7ffffe, v4
	v_cvt_u32_f32_e32 v3, v3
	v_sub_u32_e32 v4, 0, v2
	v_mul_lo_u32 v1, v4, v3
	v_mul_hi_u32 v1, v3, v1
	v_add_u32_e32 v1, v3, v1
	v_mul_hi_u32 v1, v5, v1
	v_mul_lo_u32 v3, v1, v2
	v_sub_u32_e32 v3, v5, v3
	v_add_u32_e32 v4, 1, v1
	v_cmp_ge_u32_e32 vcc, v3, v2
	s_nop 1
	v_cndmask_b32_e32 v1, v1, v4, vcc
	v_sub_u32_e32 v4, v3, v2
	v_cndmask_b32_e32 v3, v3, v4, vcc
	v_add_u32_e32 v4, 1, v1
	v_cmp_ge_u32_e32 vcc, v3, v2
	v_add_u32_e32 v3, 1, v5
	s_nop 0
	v_cndmask_b32_e32 v1, v1, v4, vcc
	v_mul_lo_u32 v4, v2, v1
	v_add_u32_e32 v2, v4, v2
	v_cmp_ne_u32_e32 vcc, v3, v2
	s_and_saveexec_b64 s[10:11], vcc
	s_xor_b64 s[10:11], exec, s[10:11]
	s_cbranch_execz .LBB0_167
	s_waitcnt lgkmcnt(0)
	v_add_u32_e32 v1, 1, v1
	v_mul_lo_u32 v1, v1, v0
	s_add_u32 s8, s6, 0x7400
	s_addc_u32 s9, s7, 0
	v_mov_b32_e32 v0, 0
	global_load_dword v2, v0, s[8:9] sc1
	s_waitcnt vmcnt(0)
	v_cmp_lt_u32_e32 vcc, v2, v1
	s_and_saveexec_b64 s[12:13], vcc
	s_cbranch_execz .LBB0_166
	s_mov_b32 s20, 1
	s_mov_b64 s[14:15], 0
	s_branch .LBB0_157

; __device__ __forceinline__ unsigned xb_ld(unsigned* p)              { return __hip_atomic_load(p, __ATOMIC_RELAXED, __HIP_MEMORY_SCOPE_AGENT); }
; #define XB_SPIN(cond, bar) do { unsigned _sp = 0; while (cond) { __builtin_amdgcn_s_sleep(1); \
;     if ((++_sp & 255u) == 0u) { if (xb_ld(&(bar)[XB_TMO])) break; if (_sp > XB_SPIN_CAP) { atomicAdd(&(bar)[XB_TMO], 1u); break; } } } } while (0)
; __device__ __forceinline__ void xcd_barrier(const XcdBarrier& b, const bool leader  ) {
;     ...
;             XB_SPIN(xb_ld(&bar[XB_XGEN(b.x)]) == gen, bar);
.LBB0_159:
	global_load_dword v2, v0, s[8:9] sc1
	s_add_i32 s20, s20, 1
	s_mov_b64 s[24:25], -1
	s_waitcnt vmcnt(0)
	v_cmp_ge_u32_e32 vcc, v2, v1
	s_orn2_b64 s[18:19], vcc, exec
	s_branch .LBB0_156

; __device__ __forceinline__ unsigned xb_ld(unsigned* p)              { return __hip_atomic_load(p, __ATOMIC_RELAXED, __HIP_MEMORY_SCOPE_AGENT); }
; __device__ __forceinline__ unsigned xb_add(unsigned* p, unsigned v) { return __hip_atomic_fetch_add(p, v, __ATOMIC_RELAXED, __HIP_MEMORY_SCOPE_AGENT); }
; #define XB_SPIN(cond, bar) do { unsigned _sp = 0; while (cond) { __builtin_amdgcn_s_sleep(1); \
;     if ((++_sp & 255u) == 0u) { if (xb_ld(&(bar)[XB_TMO])) break; if (_sp > XB_SPIN_CAP) { atomicAdd(&(bar)[XB_TMO], 1u); break; } } } } while (0)
; __device__ __forceinline__ void xcd_barrier(const XcdBarrier& b, const bool leader  ) {
;     ...
;             const unsigned og = xb_add(&bar[XB_TOP], 1u);
;             const unsigned tg = og / nx;
;             if (og + 1u == (tg + 1u) * nx) xb_add(&bar[XB_TOPGEN], 1u);
;             else XB_SPIN(xb_ld(&bar[XB_TOPGEN]) == tg, bar);
.LBB0_170:
	s_or_b64 exec, exec, s[12:13]
	v_cvt_f32_u32_e32 v3, v0
	s_waitcnt vmcnt(0)
	v_readfirstlane_b32 s10, v2
	s_add_u32 s6, s6, 0x7500
	s_addc_u32 s7, s7, 0
	v_rcp_iflag_f32_e32 v3, v3
	v_add_u32_e32 v1, s10, v1
	s_mov_b64 s[12:13], 0
	v_mul_f32_e32 v2, 0x4f7ffffe, v3
	v_cvt_u32_f32_e32 v2, v2
	v_sub_u32_e32 v3, 0, v0
	v_mul_lo_u32 v3, v3, v2
	v_mul_hi_u32 v3, v2, v3
	v_add_u32_e32 v2, v2, v3
	v_mul_hi_u32 v2, v1, v2
	v_mul_lo_u32 v3, v2, v0
	v_sub_u32_e32 v3, v1, v3
	v_add_u32_e32 v4, 1, v2
	v_cmp_ge_u32_e32 vcc, v3, v0
	v_add_u32_e32 v1, 1, v1
	s_nop 0
	v_cndmask_b32_e32 v2, v2, v4, vcc
	v_sub_u32_e32 v4, v3, v0
	v_cndmask_b32_e32 v3, v3, v4, vcc
	v_add_u32_e32 v4, 1, v2
	v_cmp_ge_u32_e32 vcc, v3, v0
	s_nop 1
	v_cndmask_b32_e32 v2, v2, v4, vcc
	v_mul_lo_u32 v3, v0, v2
	v_add_u32_e32 v0, v3, v0
	v_cmp_ne_u32_e32 vcc, v1, v0
	v_mov_b32_e32 v2, v0
	v_mov_b64_e32 v[0:1], s[6:7]
	s_and_saveexec_b64 s[10:11], vcc
	s_cbranch_execz .LBB0_182
	v_mov_b32_e32 v0, 0
	global_load_dword v1, v0, s[6:7] offset:-256 sc1
	s_mov_b64 s[14:15], 0
	s_waitcnt vmcnt(0)
	v_cmp_lt_u32_e32 vcc, v1, v2
	s_and_saveexec_b64 s[12:13], vcc
	s_cbranch_execz .LBB0_181
	s_mov_b32 s20, 1
	s_branch .LBB0_174

; __device__ __forceinline__ unsigned xb_ld(unsigned* p)              { return __hip_atomic_load(p, __ATOMIC_RELAXED, __HIP_MEMORY_SCOPE_AGENT); }
; #define XB_SPIN(cond, bar) do { unsigned _sp = 0; while (cond) { __builtin_amdgcn_s_sleep(1); \
;     if ((++_sp & 255u) == 0u) { if (xb_ld(&(bar)[XB_TMO])) break; if (_sp > XB_SPIN_CAP) { atomicAdd(&(bar)[XB_TMO], 1u); break; } } } } while (0)
; __device__ __forceinline__ void xcd_barrier(const XcdBarrier& b, const bool leader  ) {
;     ...
;             else XB_SPIN(xb_ld(&bar[XB_TOPGEN]) == tg, bar);
.LBB0_176:
	global_load_dword v1, v0, s[6:7] offset:-256 sc1
	s_add_i32 s20, s20, 1
	s_mov_b64 s[18:19], -1
	s_waitcnt vmcnt(0)
	v_cmp_ge_u32_e32 vcc, v1, v2
	s_orn2_b64 s[26:27], vcc, exec
	s_branch .LBB0_173

; __device__ __forceinline__ unsigned xb_ld(unsigned* p)              { return __hip_atomic_load(p, __ATOMIC_RELAXED, __HIP_MEMORY_SCOPE_AGENT); }
; __device__ __forceinline__ unsigned xb_add(unsigned* p, unsigned v) { return __hip_atomic_fetch_add(p, v, __ATOMIC_RELAXED, __HIP_MEMORY_SCOPE_AGENT); }
; #define XB_SPIN(cond, bar) do { unsigned _sp = 0; while (cond) { __builtin_amdgcn_s_sleep(1); \
;     if ((++_sp & 255u) == 0u) { if (xb_ld(&(bar)[XB_TMO])) break; if (_sp > XB_SPIN_CAP) { atomicAdd(&(bar)[XB_TMO], 1u); break; } } } } while (0)
; __device__ __forceinline__ void xcd_barrier(const XcdBarrier& b, const bool leader  ) {
;     ...
;         const unsigned old = xb_add(&bar[XB_XSUB(b.x)], 1u);
;         const unsigned gen = old / nloc;
;         if (old + 1u == (gen + 1u) * nloc) {
;             __builtin_amdgcn_fence(__ATOMIC_RELEASE, "agent");
;             asm volatile("s_waitcnt vmcnt(0)" ::: "memory");
;             const unsigned og = xb_add(&bar[XB_TOP], 1u);
;             const unsigned tg = og / nx;
;             if (og + 1u == (tg + 1u) * nx) xb_add(&bar[XB_TOPGEN], 1u);
;             else XB_SPIN(xb_ld(&bar[XB_TOPGEN]) == tg, bar);
;             __builtin_amdgcn_fence(__ATOMIC_ACQUIRE, "agent");
;             xb_add(&bar[XB_XGEN(b.x)], 1u);
;             asm volatile("s_waitcnt vmcnt(0)" ::: "memory");
;         } else {
;             XB_SPIN(xb_ld(&bar[XB_XGEN(b.x)]) == gen, bar);
;             __builtin_amdgcn_fence(__ATOMIC_ACQUIRE, "agent");
;             asm volatile("s_waitcnt vmcnt(0)" ::: "memory");
;         }
.LBB0_378:
	s_or_b64 exec, exec, s[14:15]
	v_cvt_f32_u32_e32 v5, v3
	s_waitcnt vmcnt(0)
	v_readfirstlane_b32 s12, v4
	s_add_u32 s10, s10, 0x2400
	s_addc_u32 s11, s11, 0
	v_rcp_iflag_f32_e32 v5, v5
	v_add_u32_e32 v6, s12, v2
	v_mul_f32_e32 v4, 0x4f7ffffe, v5
	v_cvt_u32_f32_e32 v4, v4
	v_sub_u32_e32 v5, 0, v3
	v_mul_lo_u32 v2, v5, v4
	v_mul_hi_u32 v2, v4, v2
	v_add_u32_e32 v2, v4, v2
	v_mul_hi_u32 v2, v6, v2
	v_mul_lo_u32 v4, v2, v3
	v_sub_u32_e32 v4, v6, v4
	v_add_u32_e32 v5, 1, v2
	v_cmp_ge_u32_e32 vcc, v4, v3
	s_nop 1
	v_cndmask_b32_e32 v2, v2, v5, vcc
	v_sub_u32_e32 v5, v4, v3
	v_cndmask_b32_e32 v4, v4, v5, vcc
	v_add_u32_e32 v5, 1, v2
	v_cmp_ge_u32_e32 vcc, v4, v3
	v_add_u32_e32 v4, 1, v6
	s_nop 0
	v_cndmask_b32_e32 v2, v2, v5, vcc
	v_mul_lo_u32 v5, v3, v2
	v_add_u32_e32 v3, v5, v3
	v_cmp_ne_u32_e32 vcc, v4, v3
	s_and_saveexec_b64 s[12:13], vcc
	s_xor_b64 s[12:13], exec, s[12:13]
	s_cbranch_execz .LBB0_392
	s_waitcnt lgkmcnt(0)
	v_add_u32_e32 v2, 1, v2
	v_mul_lo_u32 v2, v2, v0
	s_add_u32 s10, s6, 0x7400
	s_addc_u32 s11, s7, 0
	global_load_dword v0, v1, s[10:11] sc1
	s_waitcnt vmcnt(0)
	v_cmp_lt_u32_e32 vcc, v0, v2
	s_and_saveexec_b64 s[14:15], vcc
	s_cbranch_execz .LBB0_391
	s_mov_b32 s20, 1
	s_mov_b64 s[16:17], 0
	s_branch .LBB0_382

; __device__ __forceinline__ unsigned xb_ld(unsigned* p)              { return __hip_atomic_load(p, __ATOMIC_RELAXED, __HIP_MEMORY_SCOPE_AGENT); }
; #define XB_SPIN(cond, bar) do { unsigned _sp = 0; while (cond) { __builtin_amdgcn_s_sleep(1); \
;     if ((++_sp & 255u) == 0u) { if (xb_ld(&(bar)[XB_TMO])) break; if (_sp > XB_SPIN_CAP) { atomicAdd(&(bar)[XB_TMO], 1u); break; } } } } while (0)
; __device__ __forceinline__ void xcd_barrier(const XcdBarrier& b, const bool leader  ) {
;     ...
;             XB_SPIN(xb_ld(&bar[XB_XGEN(b.x)]) == gen, bar);
.LBB0_384:
	global_load_dword v0, v1, s[10:11] sc1
	s_add_i32 s20, s20, 1
	s_mov_b64 s[30:31], -1
	s_waitcnt vmcnt(0)
	v_cmp_ge_u32_e32 vcc, v0, v2
	s_orn2_b64 s[26:27], vcc, exec
	s_branch .LBB0_381

; __device__ __forceinline__ unsigned xb_ld(unsigned* p)              { return __hip_atomic_load(p, __ATOMIC_RELAXED, __HIP_MEMORY_SCOPE_AGENT); }
; __device__ __forceinline__ unsigned xb_add(unsigned* p, unsigned v) { return __hip_atomic_fetch_add(p, v, __ATOMIC_RELAXED, __HIP_MEMORY_SCOPE_AGENT); }
; #define XB_SPIN(cond, bar) do { unsigned _sp = 0; while (cond) { __builtin_amdgcn_s_sleep(1); \
;     if ((++_sp & 255u) == 0u) { if (xb_ld(&(bar)[XB_TMO])) break; if (_sp > XB_SPIN_CAP) { atomicAdd(&(bar)[XB_TMO], 1u); break; } } } } while (0)
; __device__ __forceinline__ void xcd_barrier(const XcdBarrier& b, const bool leader  ) {
;     ...
;             const unsigned og = xb_add(&bar[XB_TOP], 1u);
;             const unsigned tg = og / nx;
;             if (og + 1u == (tg + 1u) * nx) xb_add(&bar[XB_TOPGEN], 1u);
;             else XB_SPIN(xb_ld(&bar[XB_TOPGEN]) == tg, bar);
.LBB0_395:
	s_or_b64 exec, exec, s[14:15]
	v_cvt_f32_u32_e32 v4, v0
	s_waitcnt vmcnt(0)
	v_readfirstlane_b32 s12, v3
	s_add_u32 s6, s6, 0x7500
	s_addc_u32 s7, s7, 0
	v_rcp_iflag_f32_e32 v4, v4
	v_add_u32_e32 v2, s12, v2
	s_mov_b64 s[14:15], 0
	v_mul_f32_e32 v3, 0x4f7ffffe, v4
	v_cvt_u32_f32_e32 v3, v3
	v_sub_u32_e32 v4, 0, v0
	v_mul_lo_u32 v4, v4, v3
	v_mul_hi_u32 v4, v3, v4
	v_add_u32_e32 v3, v3, v4
	v_mul_hi_u32 v3, v2, v3
	v_mul_lo_u32 v4, v3, v0
	v_sub_u32_e32 v4, v2, v4
	v_add_u32_e32 v5, 1, v3
	v_cmp_ge_u32_e32 vcc, v4, v0
	v_add_u32_e32 v2, 1, v2
	s_nop 0
	v_cndmask_b32_e32 v3, v3, v5, vcc
	v_sub_u32_e32 v5, v4, v0
	v_cndmask_b32_e32 v4, v4, v5, vcc
	v_add_u32_e32 v5, 1, v3
	v_cmp_ge_u32_e32 vcc, v4, v0
	s_nop 1
	v_cndmask_b32_e32 v4, v3, v5, vcc
	v_mul_lo_u32 v3, v0, v4
	v_add_u32_e32 v0, v3, v0
	v_cmp_ne_u32_e32 vcc, v2, v0
	v_mov_b32_e32 v4, v0
	v_mov_b64_e32 v[2:3], s[6:7]
	s_and_saveexec_b64 s[12:13], vcc
	s_cbranch_execz .LBB0_407
	global_load_dword v0, v1, s[6:7] offset:-256 sc1
	s_mov_b64 s[16:17], 0
	s_waitcnt vmcnt(0)
	v_cmp_lt_u32_e32 vcc, v0, v4
	s_and_saveexec_b64 s[14:15], vcc
	s_cbranch_execz .LBB0_406
	s_mov_b32 s20, 1
	s_branch .LBB0_399

; __device__ __forceinline__ unsigned xb_ld(unsigned* p)              { return __hip_atomic_load(p, __ATOMIC_RELAXED, __HIP_MEMORY_SCOPE_AGENT); }
; #define XB_SPIN(cond, bar) do { unsigned _sp = 0; while (cond) { __builtin_amdgcn_s_sleep(1); \
;     if ((++_sp & 255u) == 0u) { if (xb_ld(&(bar)[XB_TMO])) break; if (_sp > XB_SPIN_CAP) { atomicAdd(&(bar)[XB_TMO], 1u); break; } } } } while (0)
; __device__ __forceinline__ void xcd_barrier(const XcdBarrier& b, const bool leader  ) {
;     ...
;             else XB_SPIN(xb_ld(&bar[XB_TOPGEN]) == tg, bar);
.LBB0_401:
	global_load_dword v0, v1, s[6:7] offset:-256 sc1
	s_add_i32 s20, s20, 1
	s_mov_b64 s[30:31], -1
	s_waitcnt vmcnt(0)
	v_cmp_ge_u32_e32 vcc, v0, v4
	s_orn2_b64 s[26:27], vcc, exec
	s_branch .LBB0_398

; __device__ __forceinline__ unsigned xb_ld(unsigned* p)              { return __hip_atomic_load(p, __ATOMIC_RELAXED, __HIP_MEMORY_SCOPE_AGENT); }
; __device__ __forceinline__ unsigned xb_add(unsigned* p, unsigned v) { return __hip_atomic_fetch_add(p, v, __ATOMIC_RELAXED, __HIP_MEMORY_SCOPE_AGENT); }
; #define XB_SPIN(cond, bar) do { unsigned _sp = 0; while (cond) { __builtin_amdgcn_s_sleep(1); \
;     if ((++_sp & 255u) == 0u) { if (xb_ld(&(bar)[XB_TMO])) break; if (_sp > XB_SPIN_CAP) { atomicAdd(&(bar)[XB_TMO], 1u); break; } } } } while (0)
; __device__ __forceinline__ void xcd_barrier(const XcdBarrier& b, const bool leader  ) {
;     ...
;         const unsigned old = xb_add(&bar[XB_XSUB(b.x)], 1u);
;         const unsigned gen = old / nloc;
;         if (old + 1u == (gen + 1u) * nloc) {
;             __builtin_amdgcn_fence(__ATOMIC_RELEASE, "agent");
;             asm volatile("s_waitcnt vmcnt(0)" ::: "memory");
;             const unsigned og = xb_add(&bar[XB_TOP], 1u);
;             const unsigned tg = og / nx;
;             if (og + 1u == (tg + 1u) * nx) xb_add(&bar[XB_TOPGEN], 1u);
;             else XB_SPIN(xb_ld(&bar[XB_TOPGEN]) == tg, bar);
;             __builtin_amdgcn_fence(__ATOMIC_ACQUIRE, "agent");
;             xb_add(&bar[XB_XGEN(b.x)], 1u);
;             asm volatile("s_waitcnt vmcnt(0)" ::: "memory");
;         } else {
;             XB_SPIN(xb_ld(&bar[XB_XGEN(b.x)]) == gen, bar);
;             __builtin_amdgcn_fence(__ATOMIC_ACQUIRE, "agent");
;             asm volatile("s_waitcnt vmcnt(0)" ::: "memory");
;         }
.LBB0_466:
	s_or_b64 exec, exec, s[16:17]
	v_cvt_f32_u32_e32 v5, v3
	s_waitcnt vmcnt(0)
	v_readfirstlane_b32 s14, v4
	s_add_u32 s12, s12, 0x2400
	s_addc_u32 s13, s13, 0
	v_rcp_iflag_f32_e32 v5, v5
	v_add_u32_e32 v6, s14, v2
	v_mul_f32_e32 v4, 0x4f7ffffe, v5
	v_cvt_u32_f32_e32 v4, v4
	v_sub_u32_e32 v5, 0, v3
	v_mul_lo_u32 v2, v5, v4
	v_mul_hi_u32 v2, v4, v2
	v_add_u32_e32 v2, v4, v2
	v_mul_hi_u32 v2, v6, v2
	v_mul_lo_u32 v4, v2, v3
	v_sub_u32_e32 v4, v6, v4
	v_add_u32_e32 v5, 1, v2
	v_cmp_ge_u32_e32 vcc, v4, v3
	s_nop 1
	v_cndmask_b32_e32 v2, v2, v5, vcc
	v_sub_u32_e32 v5, v4, v3
	v_cndmask_b32_e32 v4, v4, v5, vcc
	v_add_u32_e32 v5, 1, v2
	v_cmp_ge_u32_e32 vcc, v4, v3
	v_add_u32_e32 v4, 1, v6
	s_nop 0
	v_cndmask_b32_e32 v2, v2, v5, vcc
	v_mul_lo_u32 v5, v3, v2
	v_add_u32_e32 v3, v5, v3
	v_cmp_ne_u32_e32 vcc, v4, v3
	s_and_saveexec_b64 s[14:15], vcc
	s_xor_b64 s[14:15], exec, s[14:15]
	s_cbranch_execz .LBB0_480
	s_waitcnt lgkmcnt(0)
	v_add_u32_e32 v2, 1, v2
	v_mul_lo_u32 v2, v2, v0
	s_add_u32 s12, s10, 0x7400
	s_addc_u32 s13, s11, 0
	global_load_dword v0, v1, s[12:13] sc1
	s_waitcnt vmcnt(0)
	v_cmp_lt_u32_e32 vcc, v0, v2
	s_and_saveexec_b64 s[16:17], vcc
	s_cbranch_execz .LBB0_479
	s_mov_b32 s20, 1
	s_mov_b64 s[18:19], 0
	s_branch .LBB0_470

; __device__ __forceinline__ unsigned xb_ld(unsigned* p)              { return __hip_atomic_load(p, __ATOMIC_RELAXED, __HIP_MEMORY_SCOPE_AGENT); }
; #define XB_SPIN(cond, bar) do { unsigned _sp = 0; while (cond) { __builtin_amdgcn_s_sleep(1); \
;     if ((++_sp & 255u) == 0u) { if (xb_ld(&(bar)[XB_TMO])) break; if (_sp > XB_SPIN_CAP) { atomicAdd(&(bar)[XB_TMO], 1u); break; } } } } while (0)
; __device__ __forceinline__ void xcd_barrier(const XcdBarrier& b, const bool leader  ) {
;     ...
;             XB_SPIN(xb_ld(&bar[XB_XGEN(b.x)]) == gen, bar);
.LBB0_472:
	global_load_dword v0, v1, s[12:13] sc1
	s_add_i32 s20, s20, 1
	s_mov_b64 s[36:37], -1
	s_waitcnt vmcnt(0)
	v_cmp_ge_u32_e32 vcc, v0, v2
	s_orn2_b64 s[30:31], vcc, exec
	s_branch .LBB0_469

; __device__ __forceinline__ unsigned xb_ld(unsigned* p)              { return __hip_atomic_load(p, __ATOMIC_RELAXED, __HIP_MEMORY_SCOPE_AGENT); }
; __device__ __forceinline__ unsigned xb_add(unsigned* p, unsigned v) { return __hip_atomic_fetch_add(p, v, __ATOMIC_RELAXED, __HIP_MEMORY_SCOPE_AGENT); }
; #define XB_SPIN(cond, bar) do { unsigned _sp = 0; while (cond) { __builtin_amdgcn_s_sleep(1); \
;     if ((++_sp & 255u) == 0u) { if (xb_ld(&(bar)[XB_TMO])) break; if (_sp > XB_SPIN_CAP) { atomicAdd(&(bar)[XB_TMO], 1u); break; } } } } while (0)
; __device__ __forceinline__ void xcd_barrier(const XcdBarrier& b, const bool leader  ) {
;     ...
;             const unsigned og = xb_add(&bar[XB_TOP], 1u);
;             const unsigned tg = og / nx;
;             if (og + 1u == (tg + 1u) * nx) xb_add(&bar[XB_TOPGEN], 1u);
;             else XB_SPIN(xb_ld(&bar[XB_TOPGEN]) == tg, bar);
.LBB0_483:
	s_or_b64 exec, exec, s[16:17]
	v_cvt_f32_u32_e32 v4, v0
	s_waitcnt vmcnt(0)
	v_readfirstlane_b32 s14, v3
	s_add_u32 s10, s10, 0x7500
	s_addc_u32 s11, s11, 0
	v_rcp_iflag_f32_e32 v4, v4
	v_add_u32_e32 v2, s14, v2
	s_mov_b64 s[16:17], 0
	v_mul_f32_e32 v3, 0x4f7ffffe, v4
	v_cvt_u32_f32_e32 v3, v3
	v_sub_u32_e32 v4, 0, v0
	v_mul_lo_u32 v4, v4, v3
	v_mul_hi_u32 v4, v3, v4
	v_add_u32_e32 v3, v3, v4
	v_mul_hi_u32 v3, v2, v3
	v_mul_lo_u32 v4, v3, v0
	v_sub_u32_e32 v4, v2, v4
	v_add_u32_e32 v5, 1, v3
	v_cmp_ge_u32_e32 vcc, v4, v0
	v_add_u32_e32 v2, 1, v2
	s_nop 0
	v_cndmask_b32_e32 v3, v3, v5, vcc
	v_sub_u32_e32 v5, v4, v0
	v_cndmask_b32_e32 v4, v4, v5, vcc
	v_add_u32_e32 v5, 1, v3
	v_cmp_ge_u32_e32 vcc, v4, v0
	s_nop 1
	v_cndmask_b32_e32 v4, v3, v5, vcc
	v_mul_lo_u32 v3, v0, v4
	v_add_u32_e32 v0, v3, v0
	v_cmp_ne_u32_e32 vcc, v2, v0
	v_mov_b32_e32 v4, v0
	v_mov_b64_e32 v[2:3], s[10:11]
	s_and_saveexec_b64 s[14:15], vcc
	s_cbranch_execz .LBB0_495
	global_load_dword v0, v1, s[10:11] offset:-256 sc1
	s_mov_b64 s[18:19], 0
	s_waitcnt vmcnt(0)
	v_cmp_lt_u32_e32 vcc, v0, v4
	s_and_saveexec_b64 s[16:17], vcc
	s_cbranch_execz .LBB0_494
	s_mov_b32 s20, 1
	s_branch .LBB0_487

; __device__ __forceinline__ unsigned xb_ld(unsigned* p)              { return __hip_atomic_load(p, __ATOMIC_RELAXED, __HIP_MEMORY_SCOPE_AGENT); }
; #define XB_SPIN(cond, bar) do { unsigned _sp = 0; while (cond) { __builtin_amdgcn_s_sleep(1); \
;     if ((++_sp & 255u) == 0u) { if (xb_ld(&(bar)[XB_TMO])) break; if (_sp > XB_SPIN_CAP) { atomicAdd(&(bar)[XB_TMO], 1u); break; } } } } while (0)
; __device__ __forceinline__ void xcd_barrier(const XcdBarrier& b, const bool leader  ) {
;     ...
;             else XB_SPIN(xb_ld(&bar[XB_TOPGEN]) == tg, bar);
.LBB0_489:
	global_load_dword v0, v1, s[10:11] offset:-256 sc1
	s_add_i32 s20, s20, 1
	s_mov_b64 s[36:37], -1
	s_waitcnt vmcnt(0)
	v_cmp_ge_u32_e32 vcc, v0, v4
	s_orn2_b64 s[30:31], vcc, exec
	s_branch .LBB0_486

; __device__ __forceinline__ unsigned xb_ld(unsigned* p)              { return __hip_atomic_load(p, __ATOMIC_RELAXED, __HIP_MEMORY_SCOPE_AGENT); }
; __device__ __forceinline__ unsigned xb_add(unsigned* p, unsigned v) { return __hip_atomic_fetch_add(p, v, __ATOMIC_RELAXED, __HIP_MEMORY_SCOPE_AGENT); }
; #define XB_SPIN(cond, bar) do { unsigned _sp = 0; while (cond) { __builtin_amdgcn_s_sleep(1); \
;     if ((++_sp & 255u) == 0u) { if (xb_ld(&(bar)[XB_TMO])) break; if (_sp > XB_SPIN_CAP) { atomicAdd(&(bar)[XB_TMO], 1u); break; } } } } while (0)
; __device__ __forceinline__ void xcd_barrier(const XcdBarrier& b, const bool leader  ) {
;     ...
;         const unsigned old = xb_add(&bar[XB_XSUB(b.x)], 1u);
;         const unsigned gen = old / nloc;
;         if (old + 1u == (gen + 1u) * nloc) {
;             __builtin_amdgcn_fence(__ATOMIC_RELEASE, "agent");
;             asm volatile("s_waitcnt vmcnt(0)" ::: "memory");
;             const unsigned og = xb_add(&bar[XB_TOP], 1u);
;             const unsigned tg = og / nx;
;             if (og + 1u == (tg + 1u) * nx) xb_add(&bar[XB_TOPGEN], 1u);
;             else XB_SPIN(xb_ld(&bar[XB_TOPGEN]) == tg, bar);
;             __builtin_amdgcn_fence(__ATOMIC_ACQUIRE, "agent");
;             xb_add(&bar[XB_XGEN(b.x)], 1u);
;             asm volatile("s_waitcnt vmcnt(0)" ::: "memory");
;         } else {
;             XB_SPIN(xb_ld(&bar[XB_XGEN(b.x)]) == gen, bar);
;             __builtin_amdgcn_fence(__ATOMIC_ACQUIRE, "agent");
;             asm volatile("s_waitcnt vmcnt(0)" ::: "memory");
;         }
.LBB0_1232:
	s_or_b64 exec, exec, s[12:13]
	v_cvt_f32_u32_e32 v5, v3
	s_waitcnt vmcnt(0)
	v_readfirstlane_b32 s10, v4
	s_add_u32 s8, s8, 0x2400
	s_addc_u32 s9, s9, 0
	v_rcp_iflag_f32_e32 v5, v5
	v_add_u32_e32 v6, s10, v2
	v_mul_f32_e32 v4, 0x4f7ffffe, v5
	v_cvt_u32_f32_e32 v4, v4
	v_sub_u32_e32 v5, 0, v3
	v_mul_lo_u32 v2, v5, v4
	v_mul_hi_u32 v2, v4, v2
	v_add_u32_e32 v2, v4, v2
	v_mul_hi_u32 v2, v6, v2
	v_mul_lo_u32 v4, v2, v3
	v_sub_u32_e32 v4, v6, v4
	v_add_u32_e32 v5, 1, v2
	v_cmp_ge_u32_e32 vcc, v4, v3
	s_nop 1
	v_cndmask_b32_e32 v2, v2, v5, vcc
	v_sub_u32_e32 v5, v4, v3
	v_cndmask_b32_e32 v4, v4, v5, vcc
	v_add_u32_e32 v5, 1, v2
	v_cmp_ge_u32_e32 vcc, v4, v3
	v_add_u32_e32 v4, 1, v6
	s_nop 0
	v_cndmask_b32_e32 v2, v2, v5, vcc
	v_mul_lo_u32 v5, v3, v2
	v_add_u32_e32 v3, v5, v3
	v_cmp_ne_u32_e32 vcc, v4, v3
	s_and_saveexec_b64 s[10:11], vcc
	s_xor_b64 s[10:11], exec, s[10:11]
	s_cbranch_execz .LBB0_1246
	s_waitcnt lgkmcnt(0)
	v_add_u32_e32 v2, 1, v2
	v_mul_lo_u32 v2, v2, v0
	s_add_u32 s8, s6, 0x7400
	s_addc_u32 s9, s7, 0
	global_load_dword v0, v1, s[8:9] sc1
	s_waitcnt vmcnt(0)
	v_cmp_lt_u32_e32 vcc, v0, v2
	s_and_saveexec_b64 s[12:13], vcc
	s_cbranch_execz .LBB0_1245
	s_mov_b32 s20, 1
	s_mov_b64 s[14:15], 0
	s_branch .LBB0_1236

; __device__ __forceinline__ unsigned xb_ld(unsigned* p)              { return __hip_atomic_load(p, __ATOMIC_RELAXED, __HIP_MEMORY_SCOPE_AGENT); }
; #define XB_SPIN(cond, bar) do { unsigned _sp = 0; while (cond) { __builtin_amdgcn_s_sleep(1); \
;     if ((++_sp & 255u) == 0u) { if (xb_ld(&(bar)[XB_TMO])) break; if (_sp > XB_SPIN_CAP) { atomicAdd(&(bar)[XB_TMO], 1u); break; } } } } while (0)
; __device__ __forceinline__ void xcd_barrier(const XcdBarrier& b, const bool leader  ) {
;     ...
;             XB_SPIN(xb_ld(&bar[XB_XGEN(b.x)]) == gen, bar);
.LBB0_1238:
	global_load_dword v0, v1, s[8:9] sc1
	s_add_i32 s20, s20, 1
	s_mov_b64 s[26:27], -1
	s_waitcnt vmcnt(0)
	v_cmp_ge_u32_e32 vcc, v0, v2
	s_orn2_b64 s[18:19], vcc, exec
	s_branch .LBB0_1235

; __device__ __forceinline__ unsigned xb_ld(unsigned* p)              { return __hip_atomic_load(p, __ATOMIC_RELAXED, __HIP_MEMORY_SCOPE_AGENT); }
; __device__ __forceinline__ unsigned xb_add(unsigned* p, unsigned v) { return __hip_atomic_fetch_add(p, v, __ATOMIC_RELAXED, __HIP_MEMORY_SCOPE_AGENT); }
; #define XB_SPIN(cond, bar) do { unsigned _sp = 0; while (cond) { __builtin_amdgcn_s_sleep(1); \
;     if ((++_sp & 255u) == 0u) { if (xb_ld(&(bar)[XB_TMO])) break; if (_sp > XB_SPIN_CAP) { atomicAdd(&(bar)[XB_TMO], 1u); break; } } } } while (0)
; __device__ __forceinline__ void xcd_barrier(const XcdBarrier& b, const bool leader  ) {
;     ...
;             const unsigned og = xb_add(&bar[XB_TOP], 1u);
;             const unsigned tg = og / nx;
;             if (og + 1u == (tg + 1u) * nx) xb_add(&bar[XB_TOPGEN], 1u);
;             else XB_SPIN(xb_ld(&bar[XB_TOPGEN]) == tg, bar);
.LBB0_1249:
	s_or_b64 exec, exec, s[12:13]
	v_cvt_f32_u32_e32 v4, v0
	s_waitcnt vmcnt(0)
	v_readfirstlane_b32 s10, v3
	s_add_u32 s6, s6, 0x7500
	s_addc_u32 s7, s7, 0
	v_rcp_iflag_f32_e32 v4, v4
	v_add_u32_e32 v2, s10, v2
	s_mov_b64 s[12:13], 0
	v_mul_f32_e32 v3, 0x4f7ffffe, v4
	v_cvt_u32_f32_e32 v3, v3
	v_sub_u32_e32 v4, 0, v0
	v_mul_lo_u32 v4, v4, v3
	v_mul_hi_u32 v4, v3, v4
	v_add_u32_e32 v3, v3, v4
	v_mul_hi_u32 v3, v2, v3
	v_mul_lo_u32 v4, v3, v0
	v_sub_u32_e32 v4, v2, v4
	v_add_u32_e32 v5, 1, v3
	v_cmp_ge_u32_e32 vcc, v4, v0
	v_add_u32_e32 v2, 1, v2
	s_nop 0
	v_cndmask_b32_e32 v3, v3, v5, vcc
	v_sub_u32_e32 v5, v4, v0
	v_cndmask_b32_e32 v4, v4, v5, vcc
	v_add_u32_e32 v5, 1, v3
	v_cmp_ge_u32_e32 vcc, v4, v0
	s_nop 1
	v_cndmask_b32_e32 v4, v3, v5, vcc
	v_mul_lo_u32 v3, v0, v4
	v_add_u32_e32 v0, v3, v0
	v_cmp_ne_u32_e32 vcc, v2, v0
	v_mov_b32_e32 v4, v0
	v_mov_b64_e32 v[2:3], s[6:7]
	s_and_saveexec_b64 s[10:11], vcc
	s_cbranch_execz .LBB0_1261
	global_load_dword v0, v1, s[6:7] offset:-256 sc1
	s_mov_b64 s[14:15], 0
	s_waitcnt vmcnt(0)
	v_cmp_lt_u32_e32 vcc, v0, v4
	s_and_saveexec_b64 s[12:13], vcc
	s_cbranch_execz .LBB0_1260
	s_mov_b32 s20, 1
	s_branch .LBB0_1253

; __device__ __forceinline__ unsigned xb_ld(unsigned* p)              { return __hip_atomic_load(p, __ATOMIC_RELAXED, __HIP_MEMORY_SCOPE_AGENT); }
; #define XB_SPIN(cond, bar) do { unsigned _sp = 0; while (cond) { __builtin_amdgcn_s_sleep(1); \
;     if ((++_sp & 255u) == 0u) { if (xb_ld(&(bar)[XB_TMO])) break; if (_sp > XB_SPIN_CAP) { atomicAdd(&(bar)[XB_TMO], 1u); break; } } } } while (0)
; __device__ __forceinline__ void xcd_barrier(const XcdBarrier& b, const bool leader  ) {
;     ...
;             else XB_SPIN(xb_ld(&bar[XB_TOPGEN]) == tg, bar);
.LBB0_1255:
	global_load_dword v0, v1, s[6:7] offset:-256 sc1
	s_add_i32 s20, s20, 1
	s_mov_b64 s[26:27], -1
	s_waitcnt vmcnt(0)
	v_cmp_ge_u32_e32 vcc, v0, v4
	s_orn2_b64 s[18:19], vcc, exec
	s_branch .LBB0_1252

; __device__ __forceinline__ unsigned xb_ld(unsigned* p)              { return __hip_atomic_load(p, __ATOMIC_RELAXED, __HIP_MEMORY_SCOPE_AGENT); }
; __device__ __forceinline__ unsigned xb_add(unsigned* p, unsigned v) { return __hip_atomic_fetch_add(p, v, __ATOMIC_RELAXED, __HIP_MEMORY_SCOPE_AGENT); }
; #define XB_SPIN(cond, bar) do { unsigned _sp = 0; while (cond) { __builtin_amdgcn_s_sleep(1); \
;     if ((++_sp & 255u) == 0u) { if (xb_ld(&(bar)[XB_TMO])) break; if (_sp > XB_SPIN_CAP) { atomicAdd(&(bar)[XB_TMO], 1u); break; } } } } while (0)
; __device__ __forceinline__ void xcd_barrier(const XcdBarrier& b, const bool leader  ) {
;     ...
;         const unsigned old = xb_add(&bar[XB_XSUB(b.x)], 1u);
;         const unsigned gen = old / nloc;
;         if (old + 1u == (gen + 1u) * nloc) {
;             __builtin_amdgcn_fence(__ATOMIC_RELEASE, "agent");
;             asm volatile("s_waitcnt vmcnt(0)" ::: "memory");
;             const unsigned og = xb_add(&bar[XB_TOP], 1u);
;             const unsigned tg = og / nx;
;             if (og + 1u == (tg + 1u) * nx) xb_add(&bar[XB_TOPGEN], 1u);
;             else XB_SPIN(xb_ld(&bar[XB_TOPGEN]) == tg, bar);
;             __builtin_amdgcn_fence(__ATOMIC_ACQUIRE, "agent");
;             xb_add(&bar[XB_XGEN(b.x)], 1u);
;             asm volatile("s_waitcnt vmcnt(0)" ::: "memory");
;         } else {
;             XB_SPIN(xb_ld(&bar[XB_XGEN(b.x)]) == gen, bar);
;             __builtin_amdgcn_fence(__ATOMIC_ACQUIRE, "agent");
;             asm volatile("s_waitcnt vmcnt(0)" ::: "memory");
;         }
.LBB0_1704:
	s_or_b64 exec, exec, s[26:27]
	v_cvt_f32_u32_e32 v5, v3
	s_waitcnt vmcnt(0)
	v_readfirstlane_b32 s14, v4
	s_add_u32 s16, s16, 0x2400
	s_addc_u32 s17, s17, 0
	v_rcp_iflag_f32_e32 v5, v5
	v_add_u32_e32 v6, s14, v2
	v_mul_f32_e32 v4, 0x4f7ffffe, v5
	v_cvt_u32_f32_e32 v4, v4
	v_sub_u32_e32 v5, 0, v3
	v_mul_lo_u32 v2, v5, v4
	v_mul_hi_u32 v2, v4, v2
	v_add_u32_e32 v2, v4, v2
	v_mul_hi_u32 v2, v6, v2
	v_mul_lo_u32 v4, v2, v3
	v_sub_u32_e32 v4, v6, v4
	v_add_u32_e32 v5, 1, v2
	v_cmp_ge_u32_e32 vcc, v4, v3
	s_nop 1
	v_cndmask_b32_e32 v2, v2, v5, vcc
	v_sub_u32_e32 v5, v4, v3
	v_cndmask_b32_e32 v4, v4, v5, vcc
	v_add_u32_e32 v5, 1, v2
	v_cmp_ge_u32_e32 vcc, v4, v3
	v_add_u32_e32 v4, 1, v6
	s_nop 0
	v_cndmask_b32_e32 v2, v2, v5, vcc
	v_mul_lo_u32 v5, v3, v2
	v_add_u32_e32 v3, v5, v3
	v_cmp_ne_u32_e32 vcc, v4, v3
	s_and_saveexec_b64 s[14:15], vcc
	s_xor_b64 s[18:19], exec, s[14:15]
	s_cbranch_execz .LBB0_1718
	s_waitcnt lgkmcnt(0)
	v_add_u32_e32 v2, 1, v2
	v_mul_lo_u32 v2, v2, v0
	s_add_u32 s16, s8, 0x7400
	s_addc_u32 s17, s9, 0
	global_load_dword v0, v1, s[16:17] sc1
	s_waitcnt vmcnt(0)
	v_cmp_lt_u32_e32 vcc, v0, v2
	s_and_saveexec_b64 s[26:27], vcc
	s_cbranch_execz .LBB0_1717
	s_mov_b32 s14, 1
	s_mov_b64 s[30:31], 0
	s_branch .LBB0_1708

; __device__ __forceinline__ unsigned xb_ld(unsigned* p)              { return __hip_atomic_load(p, __ATOMIC_RELAXED, __HIP_MEMORY_SCOPE_AGENT); }
; #define XB_SPIN(cond, bar) do { unsigned _sp = 0; while (cond) { __builtin_amdgcn_s_sleep(1); \
;     if ((++_sp & 255u) == 0u) { if (xb_ld(&(bar)[XB_TMO])) break; if (_sp > XB_SPIN_CAP) { atomicAdd(&(bar)[XB_TMO], 1u); break; } } } } while (0)
; __device__ __forceinline__ void xcd_barrier(const XcdBarrier& b, const bool leader  ) {
;     ...
;             XB_SPIN(xb_ld(&bar[XB_XGEN(b.x)]) == gen, bar);
.LBB0_1710:
	global_load_dword v0, v1, s[16:17] sc1
	s_add_i32 s14, s14, 1
	s_mov_b64 s[40:41], -1
	s_waitcnt vmcnt(0)
	v_cmp_ge_u32_e32 vcc, v0, v2
	s_orn2_b64 s[38:39], vcc, exec
	s_branch .LBB0_1707

; __device__ __forceinline__ unsigned xb_ld(unsigned* p)              { return __hip_atomic_load(p, __ATOMIC_RELAXED, __HIP_MEMORY_SCOPE_AGENT); }
; __device__ __forceinline__ unsigned xb_add(unsigned* p, unsigned v) { return __hip_atomic_fetch_add(p, v, __ATOMIC_RELAXED, __HIP_MEMORY_SCOPE_AGENT); }
; #define XB_SPIN(cond, bar) do { unsigned _sp = 0; while (cond) { __builtin_amdgcn_s_sleep(1); \
;     if ((++_sp & 255u) == 0u) { if (xb_ld(&(bar)[XB_TMO])) break; if (_sp > XB_SPIN_CAP) { atomicAdd(&(bar)[XB_TMO], 1u); break; } } } } while (0)
; __device__ __forceinline__ void xcd_barrier(const XcdBarrier& b, const bool leader  ) {
;     ...
;             const unsigned og = xb_add(&bar[XB_TOP], 1u);
;             const unsigned tg = og / nx;
;             if (og + 1u == (tg + 1u) * nx) xb_add(&bar[XB_TOPGEN], 1u);
;             else XB_SPIN(xb_ld(&bar[XB_TOPGEN]) == tg, bar);
.LBB0_1721:
	s_or_b64 exec, exec, s[26:27]
	v_cvt_f32_u32_e32 v4, v0
	s_waitcnt vmcnt(0)
	v_readfirstlane_b32 s14, v3
	s_add_u32 s8, s8, 0x7500
	s_addc_u32 s9, s9, 0
	v_rcp_iflag_f32_e32 v4, v4
	v_add_u32_e32 v2, s14, v2
	s_mov_b64 s[26:27], 0
	v_mul_f32_e32 v3, 0x4f7ffffe, v4
	v_cvt_u32_f32_e32 v3, v3
	v_sub_u32_e32 v4, 0, v0
	v_mul_lo_u32 v4, v4, v3
	v_mul_hi_u32 v4, v3, v4
	v_add_u32_e32 v3, v3, v4
	v_mul_hi_u32 v3, v2, v3
	v_mul_lo_u32 v4, v3, v0
	v_sub_u32_e32 v4, v2, v4
	v_add_u32_e32 v5, 1, v3
	v_cmp_ge_u32_e32 vcc, v4, v0
	v_add_u32_e32 v2, 1, v2
	s_nop 0
	v_cndmask_b32_e32 v3, v3, v5, vcc
	v_sub_u32_e32 v5, v4, v0
	v_cndmask_b32_e32 v4, v4, v5, vcc
	v_add_u32_e32 v5, 1, v3
	v_cmp_ge_u32_e32 vcc, v4, v0
	s_nop 1
	v_cndmask_b32_e32 v4, v3, v5, vcc
	v_mul_lo_u32 v3, v0, v4
	v_add_u32_e32 v0, v3, v0
	v_cmp_ne_u32_e32 vcc, v2, v0
	v_mov_b32_e32 v4, v0
	v_mov_b64_e32 v[2:3], s[8:9]
	s_and_saveexec_b64 s[18:19], vcc
	s_cbranch_execz .LBB0_1742
	global_load_dword v0, v1, s[8:9] offset:-256 sc1
	s_mov_b64 s[30:31], 0
	s_waitcnt vmcnt(0)
	v_cmp_lt_u32_e32 vcc, v0, v4
	s_and_saveexec_b64 s[26:27], vcc
	s_cbranch_execz .LBB0_1741
	s_mov_b32 s14, 1
	s_branch .LBB0_1725

; __device__ __forceinline__ unsigned xb_ld(unsigned* p)              { return __hip_atomic_load(p, __ATOMIC_RELAXED, __HIP_MEMORY_SCOPE_AGENT); }
; #define XB_SPIN(cond, bar) do { unsigned _sp = 0; while (cond) { __builtin_amdgcn_s_sleep(1); \
;     if ((++_sp & 255u) == 0u) { if (xb_ld(&(bar)[XB_TMO])) break; if (_sp > XB_SPIN_CAP) { atomicAdd(&(bar)[XB_TMO], 1u); break; } } } } while (0)
; __device__ __forceinline__ void xcd_barrier(const XcdBarrier& b, const bool leader  ) {
;     ...
;             else XB_SPIN(xb_ld(&bar[XB_TOPGEN]) == tg, bar);
.LBB0_1727:
	global_load_dword v0, v1, s[8:9] offset:-256 sc1
	s_add_i32 s14, s14, 1
	s_mov_b64 s[40:41], -1
	s_waitcnt vmcnt(0)
	v_cmp_ge_u32_e32 vcc, v0, v4
	s_orn2_b64 s[38:39], vcc, exec
	s_branch .LBB0_1724

; __device__ __forceinline__ unsigned xb_ld(unsigned* p)              { return __hip_atomic_load(p, __ATOMIC_RELAXED, __HIP_MEMORY_SCOPE_AGENT); }
; __device__ __forceinline__ unsigned xb_add(unsigned* p, unsigned v) { return __hip_atomic_fetch_add(p, v, __ATOMIC_RELAXED, __HIP_MEMORY_SCOPE_AGENT); }
; #define XB_SPIN(cond, bar) do { unsigned _sp = 0; while (cond) { __builtin_amdgcn_s_sleep(1); \
;     if ((++_sp & 255u) == 0u) { if (xb_ld(&(bar)[XB_TMO])) break; if (_sp > XB_SPIN_CAP) { atomicAdd(&(bar)[XB_TMO], 1u); break; } } } } while (0)
; __device__ __forceinline__ void xcd_barrier(const XcdBarrier& b, const bool leader  ) {
;     ...
;         const unsigned old = xb_add(&bar[XB_XSUB(b.x)], 1u);
;         const unsigned gen = old / nloc;
;         if (old + 1u == (gen + 1u) * nloc) {
;             __builtin_amdgcn_fence(__ATOMIC_RELEASE, "agent");
;             asm volatile("s_waitcnt vmcnt(0)" ::: "memory");
;             const unsigned og = xb_add(&bar[XB_TOP], 1u);
;             const unsigned tg = og / nx;
;             if (og + 1u == (tg + 1u) * nx) xb_add(&bar[XB_TOPGEN], 1u);
;             else XB_SPIN(xb_ld(&bar[XB_TOPGEN]) == tg, bar);
;             __builtin_amdgcn_fence(__ATOMIC_ACQUIRE, "agent");
;             xb_add(&bar[XB_XGEN(b.x)], 1u);
;             asm volatile("s_waitcnt vmcnt(0)" ::: "memory");
;         } else {
;             XB_SPIN(xb_ld(&bar[XB_XGEN(b.x)]) == gen, bar);
;             __builtin_amdgcn_fence(__ATOMIC_ACQUIRE, "agent");
;             asm volatile("s_waitcnt vmcnt(0)" ::: "memory");
;         }
.LBB0_1796:
	s_or_b64 exec, exec, s[36:37]
	v_cvt_f32_u32_e32 v5, v3
	s_waitcnt vmcnt(0)
	v_readfirstlane_b32 s14, v4
	s_add_u32 s8, s8, 0x2400
	s_addc_u32 s9, s9, 0
	v_rcp_iflag_f32_e32 v5, v5
	v_add_u32_e32 v6, s14, v2
	v_mul_f32_e32 v4, 0x4f7ffffe, v5
	v_cvt_u32_f32_e32 v4, v4
	v_sub_u32_e32 v5, 0, v3
	v_mul_lo_u32 v2, v5, v4
	v_mul_hi_u32 v2, v4, v2
	v_add_u32_e32 v2, v4, v2
	v_mul_hi_u32 v2, v6, v2
	v_mul_lo_u32 v4, v2, v3
	v_sub_u32_e32 v4, v6, v4
	v_add_u32_e32 v5, 1, v2
	v_cmp_ge_u32_e32 vcc, v4, v3
	s_nop 1
	v_cndmask_b32_e32 v2, v2, v5, vcc
	v_sub_u32_e32 v5, v4, v3
	v_cndmask_b32_e32 v4, v4, v5, vcc
	v_add_u32_e32 v5, 1, v2
	v_cmp_ge_u32_e32 vcc, v4, v3
	v_add_u32_e32 v4, 1, v6
	s_nop 0
	v_cndmask_b32_e32 v2, v2, v5, vcc
	v_mul_lo_u32 v5, v3, v2
	v_add_u32_e32 v3, v5, v3
	v_cmp_ne_u32_e32 vcc, v4, v3
	s_and_saveexec_b64 s[22:23], vcc
	s_xor_b64 s[30:31], exec, s[22:23]
	s_cbranch_execz .LBB0_1810
	s_waitcnt lgkmcnt(0)
	v_add_u32_e32 v2, 1, v2
	v_mul_lo_u32 v2, v2, v0
	s_add_u32 s8, s6, 0x7400
	s_addc_u32 s9, s7, 0
	global_load_dword v0, v1, s[8:9] sc1
	s_waitcnt vmcnt(0)
	v_cmp_lt_u32_e32 vcc, v0, v2
	s_and_saveexec_b64 s[36:37], vcc
	s_cbranch_execz .LBB0_1809
	s_mov_b32 s14, 1
	s_mov_b64 s[38:39], 0
	s_branch .LBB0_1800

; __device__ __forceinline__ unsigned xb_ld(unsigned* p)              { return __hip_atomic_load(p, __ATOMIC_RELAXED, __HIP_MEMORY_SCOPE_AGENT); }
; #define XB_SPIN(cond, bar) do { unsigned _sp = 0; while (cond) { __builtin_amdgcn_s_sleep(1); \
;     if ((++_sp & 255u) == 0u) { if (xb_ld(&(bar)[XB_TMO])) break; if (_sp > XB_SPIN_CAP) { atomicAdd(&(bar)[XB_TMO], 1u); break; } } } } while (0)
; __device__ __forceinline__ void xcd_barrier(const XcdBarrier& b, const bool leader  ) {
;     ...
;             XB_SPIN(xb_ld(&bar[XB_XGEN(b.x)]) == gen, bar);
.LBB0_1802:
	global_load_dword v0, v1, s[8:9] sc1
	s_add_i32 s14, s14, 1
	s_mov_b64 s[46:47], -1
	s_waitcnt vmcnt(0)
	v_cmp_ge_u32_e32 vcc, v0, v2
	s_orn2_b64 s[42:43], vcc, exec
	s_branch .LBB0_1799

; __device__ __forceinline__ unsigned xb_ld(unsigned* p)              { return __hip_atomic_load(p, __ATOMIC_RELAXED, __HIP_MEMORY_SCOPE_AGENT); }
; __device__ __forceinline__ unsigned xb_add(unsigned* p, unsigned v) { return __hip_atomic_fetch_add(p, v, __ATOMIC_RELAXED, __HIP_MEMORY_SCOPE_AGENT); }
; #define XB_SPIN(cond, bar) do { unsigned _sp = 0; while (cond) { __builtin_amdgcn_s_sleep(1); \
;     if ((++_sp & 255u) == 0u) { if (xb_ld(&(bar)[XB_TMO])) break; if (_sp > XB_SPIN_CAP) { atomicAdd(&(bar)[XB_TMO], 1u); break; } } } } while (0)
; __device__ __forceinline__ void xcd_barrier(const XcdBarrier& b, const bool leader  ) {
;     ...
;             const unsigned og = xb_add(&bar[XB_TOP], 1u);
;             const unsigned tg = og / nx;
;             if (og + 1u == (tg + 1u) * nx) xb_add(&bar[XB_TOPGEN], 1u);
;             else XB_SPIN(xb_ld(&bar[XB_TOPGEN]) == tg, bar);
.LBB0_1813:
	s_or_b64 exec, exec, s[36:37]
	v_cvt_f32_u32_e32 v4, v0
	s_waitcnt vmcnt(0)
	v_readfirstlane_b32 s14, v3
	s_add_u32 s6, s6, 0x7500
	s_addc_u32 s7, s7, 0
	v_rcp_iflag_f32_e32 v4, v4
	v_add_u32_e32 v2, s14, v2
	s_mov_b64 s[36:37], 0
	v_mul_f32_e32 v3, 0x4f7ffffe, v4
	v_cvt_u32_f32_e32 v3, v3
	v_sub_u32_e32 v4, 0, v0
	v_mul_lo_u32 v4, v4, v3
	v_mul_hi_u32 v4, v3, v4
	v_add_u32_e32 v3, v3, v4
	v_mul_hi_u32 v3, v2, v3
	v_mul_lo_u32 v4, v3, v0
	v_sub_u32_e32 v4, v2, v4
	v_add_u32_e32 v5, 1, v3
	v_cmp_ge_u32_e32 vcc, v4, v0
	v_add_u32_e32 v2, 1, v2
	s_nop 0
	v_cndmask_b32_e32 v3, v3, v5, vcc
	v_sub_u32_e32 v5, v4, v0
	v_cndmask_b32_e32 v4, v4, v5, vcc
	v_add_u32_e32 v5, 1, v3
	v_cmp_ge_u32_e32 vcc, v4, v0
	s_nop 1
	v_cndmask_b32_e32 v4, v3, v5, vcc
	v_mul_lo_u32 v3, v0, v4
	v_add_u32_e32 v0, v3, v0
	v_cmp_ne_u32_e32 vcc, v2, v0
	v_mov_b32_e32 v4, v0
	v_mov_b64_e32 v[2:3], s[6:7]
	s_and_saveexec_b64 s[30:31], vcc
	s_cbranch_execz .LBB0_1825
	global_load_dword v0, v1, s[6:7] offset:-256 sc1
	s_mov_b64 s[38:39], 0
	s_waitcnt vmcnt(0)
	v_cmp_lt_u32_e32 vcc, v0, v4
	s_and_saveexec_b64 s[36:37], vcc
	s_cbranch_execz .LBB0_1824
	s_mov_b32 s14, 1
	s_branch .LBB0_1817

; __device__ __forceinline__ unsigned xb_ld(unsigned* p)              { return __hip_atomic_load(p, __ATOMIC_RELAXED, __HIP_MEMORY_SCOPE_AGENT); }
; #define XB_SPIN(cond, bar) do { unsigned _sp = 0; while (cond) { __builtin_amdgcn_s_sleep(1); \
;     if ((++_sp & 255u) == 0u) { if (xb_ld(&(bar)[XB_TMO])) break; if (_sp > XB_SPIN_CAP) { atomicAdd(&(bar)[XB_TMO], 1u); break; } } } } while (0)
; __device__ __forceinline__ void xcd_barrier(const XcdBarrier& b, const bool leader  ) {
;     ...
;             else XB_SPIN(xb_ld(&bar[XB_TOPGEN]) == tg, bar);
.LBB0_1819:
	global_load_dword v0, v1, s[6:7] offset:-256 sc1
	s_add_i32 s14, s14, 1
	s_mov_b64 s[46:47], -1
	s_waitcnt vmcnt(0)
	v_cmp_ge_u32_e32 vcc, v0, v4
	s_orn2_b64 s[42:43], vcc, exec
	s_branch .LBB0_1816

; __device__ __forceinline__ unsigned xb_ld(unsigned* p)              { return __hip_atomic_load(p, __ATOMIC_RELAXED, __HIP_MEMORY_SCOPE_AGENT); }
; __device__ __forceinline__ unsigned xb_add(unsigned* p, unsigned v) { return __hip_atomic_fetch_add(p, v, __ATOMIC_RELAXED, __HIP_MEMORY_SCOPE_AGENT); }
; #define XB_SPIN(cond, bar) do { unsigned _sp = 0; while (cond) { __builtin_amdgcn_s_sleep(1); \
;     if ((++_sp & 255u) == 0u) { if (xb_ld(&(bar)[XB_TMO])) break; if (_sp > XB_SPIN_CAP) { atomicAdd(&(bar)[XB_TMO], 1u); break; } } } } while (0)
; __device__ __forceinline__ void xcd_barrier(const XcdBarrier& b, const bool leader  ) {
;     ...
;         const unsigned old = xb_add(&bar[XB_XSUB(b.x)], 1u);
;         const unsigned gen = old / nloc;
;         if (old + 1u == (gen + 1u) * nloc) {
;             __builtin_amdgcn_fence(__ATOMIC_RELEASE, "agent");
;             asm volatile("s_waitcnt vmcnt(0)" ::: "memory");
;             const unsigned og = xb_add(&bar[XB_TOP], 1u);
;             const unsigned tg = og / nx;
;             if (og + 1u == (tg + 1u) * nx) xb_add(&bar[XB_TOPGEN], 1u);
;             else XB_SPIN(xb_ld(&bar[XB_TOPGEN]) == tg, bar);
;             __builtin_amdgcn_fence(__ATOMIC_ACQUIRE, "agent");
;             xb_add(&bar[XB_XGEN(b.x)], 1u);
;             asm volatile("s_waitcnt vmcnt(0)" ::: "memory");
;         } else {
;             XB_SPIN(xb_ld(&bar[XB_XGEN(b.x)]) == gen, bar);
;             __builtin_amdgcn_fence(__ATOMIC_ACQUIRE, "agent");
;             asm volatile("s_waitcnt vmcnt(0)" ::: "memory");
;         }
.LBB0_1988:
	s_or_b64 exec, exec, s[36:37]
	v_cvt_f32_u32_e32 v5, v3
	s_waitcnt vmcnt(0)
	v_readfirstlane_b32 s14, v4
	s_add_u32 s8, s8, 0x2400
	s_addc_u32 s9, s9, 0
	v_rcp_iflag_f32_e32 v5, v5
	v_add_u32_e32 v6, s14, v2
	v_mul_f32_e32 v4, 0x4f7ffffe, v5
	v_cvt_u32_f32_e32 v4, v4
	v_sub_u32_e32 v5, 0, v3
	v_mul_lo_u32 v2, v5, v4
	v_mul_hi_u32 v2, v4, v2
	v_add_u32_e32 v2, v4, v2
	v_mul_hi_u32 v2, v6, v2
	v_mul_lo_u32 v4, v2, v3
	v_sub_u32_e32 v4, v6, v4
	v_add_u32_e32 v5, 1, v2
	v_cmp_ge_u32_e32 vcc, v4, v3
	s_nop 1
	v_cndmask_b32_e32 v2, v2, v5, vcc
	v_sub_u32_e32 v5, v4, v3
	v_cndmask_b32_e32 v4, v4, v5, vcc
	v_add_u32_e32 v5, 1, v2
	v_cmp_ge_u32_e32 vcc, v4, v3
	v_add_u32_e32 v4, 1, v6
	s_nop 0
	v_cndmask_b32_e32 v2, v2, v5, vcc
	v_mul_lo_u32 v5, v3, v2
	v_add_u32_e32 v3, v5, v3
	v_cmp_ne_u32_e32 vcc, v4, v3
	s_and_saveexec_b64 s[16:17], vcc
	s_xor_b64 s[30:31], exec, s[16:17]
	s_cbranch_execz .LBB0_2002
	s_waitcnt lgkmcnt(0)
	v_add_u32_e32 v2, 1, v2
	v_mul_lo_u32 v2, v2, v0
	s_add_u32 s8, s6, 0x7400
	s_addc_u32 s9, s7, 0
	global_load_dword v0, v1, s[8:9] sc1
	s_waitcnt vmcnt(0)
	v_cmp_lt_u32_e32 vcc, v0, v2
	s_and_saveexec_b64 s[36:37], vcc
	s_cbranch_execz .LBB0_2001
	s_mov_b32 s14, 1
	s_mov_b64 s[38:39], 0
	s_branch .LBB0_1992
